# v34 plus attention unit prologue: compiler's vmcnt(0) after the counted vmcnt(4) removed (tile-2 loads stay in flight)
# baseline (speedup 1.0000x reference)
; __device__ __forceinline__ int v_st(int k, int c) { const int kk = (k & ~0xC) | ((k & 4) << 1) | ((k & 8) >> 1); return ((kk >> 3) * 4 + (c >> 5)) * 512 + ((kk & 7) * 32 + (c & 31)) * 2; }
; __device__ __forceinline__ int v_rd_base(int lane) { return ((lane & 3) << 3) | (((lane >> 2) & 3) << 6) | (((lane >> 4) & 1) << 5) | (((lane >> 5) & 1) << 8); }
; #define SWRITE(b, i) do { *(bf16x8*)((char*)V_lds + (b) * SHM_V + vst0) = sr_[i].vs0;          \
;     *(bf16x8*)((char*)V_lds + (b) * SHM_V + vst1) = sr_[i].vs1; int kc = sc * 2;               \
;     *(bf16x8*)((char*)K_lds + (b) * SHM_K + KSWZ(sr, kc)) = sr_[i].ks0;                       \
;     *(bf16x8*)((char*)K_lds + (b) * SHM_K + KSWZ(32 + sr, kc)) = sr_[i].ks1; } while (0)
; __device__ __forceinline__ void attn_body(const bf16_t* __restrict__ Qb, const bf16_t* __restrict__ Kh, const bf16_t* __restrict__ Vh,
;                                           bf16_t* __restrict__ Ob, const bf16_t* __restrict__ AGb, int seq, char* lds) {
;     ...
;   const bf16_t* Qw = Qb + (long)(wid * QBLK + r32) * LDQ + hi * 8;
; #pragma unroll
;   for (int d0 = 0; d0 < 8; ++d0) qr[d0] = *reinterpret_cast<const bf16x8*>(Qw + d0 * 16);
;   const int sr = tid >> 4, sc = (tid & 15) * 8, vst0 = v_st(sr, sc), vst1 = v_st(32 + sr, sc);
;   const int vb0 = (int)(uintptr_t)V_lds + v_rd_base(lane);
;   const unsigned goff0 = (unsigned)(sr * LDK + sc) * 2u, goff1 = (unsigned)((32 + sr) * LDK + sc) * 2u;
;   struct { bf16x8 vs0, vs1, ks0, ks1; } sr_[2];
;     ...
;   f32x16 pA0, pA1, pB0, pB1; float mnA, mnB, alA, alB; bf16x8 pa0, pa1, pa2, pa3; const int NT = seq / KVBLK;
;   constexpr int SE = 0, SO = 1;
;   SLOAD(SE, 0); asm volatile("s_waitcnt vmcnt(0)" ::: "memory"); SWRITE(0, SE); __syncthreads();
;   qkt(pA0, pA1, K_lds, qr, r32, hi); partialSM(pA0, pA1, m_reg, mnA, alA);
.LBB0_198:
	s_lshr_b32 s23, s3, 2
	s_mul_i32 s1, s18, 0x8800
	s_mul_hi_i32 s0, s18, 0x8800
	s_add_u32 s26, s8, s1
	s_addc_u32 s27, s9, s0
	s_lshl_b32 s28, s3, 7
	s_lshl_b32 s0, s3, 8
	s_add_u32 s20, s26, s0
	s_addc_u32 s21, s27, 0
	s_mul_hi_u32 s22, s23, 0x210000
	s_mul_i32 s23, s23, 0x210000
	v_mov_b32_e32 v64, v190
	s_add_u32 s4, s12, s23
	s_addc_u32 s5, s13, s22
	v_ashrrev_i32_e32 v18, 4, v64
	v_lshlrev_b32_e32 v19, 3, v64
	v_and_b32_e32 v0, 0x78, v19
	v_add_u32_e32 v21, 32, v18
	s_add_u32 s0, s10, s23
	v_lshlrev_b32_e32 v20, 1, v0
	v_lshlrev_b32_e32 v22, 8, v18
	v_lshlrev_b32_e32 v23, 8, v21
	s_addc_u32 s1, s11, s22
	v_or_b32_e32 v96, v20, v22
	v_or_b32_e32 v184, v23, v20
	v_mov_b32_e32 v185, v97
	v_lshl_add_u64 v[0:1], s[0:1], 0, v[96:97]
	v_lshl_add_u64 v[4:5], s[0:1], 0, v[184:185]
	v_lshl_add_u64 v[8:9], s[4:5], 0, v[96:97]
	v_lshl_add_u64 v[12:13], s[4:5], 0, v[184:185]
	global_load_dwordx4 v[0:3], v[0:1], off
	s_nop 0
	global_load_dwordx4 v[4:7], v[4:5], off
	s_nop 0
	global_load_dwordx4 v[8:11], v[8:9], off
	s_nop 0
	global_load_dwordx4 v[12:15], v[12:13], off
	v_ashrrev_i32_e32 v48, 1, v64
	s_movk_i32 s3, 0xffe0
	v_bfe_u32 v197, v64, 5, 1
	v_bfi_b32 v24, s3, v48, v64
	v_mov_b64_e32 v[16:17], s[20:21]
	v_mad_i64_i32 v[16:17], s[20:21], v24, s33, v[16:17]
	v_lshlrev_b32_e32 v180, 4, v197
	v_mov_b32_e32 v181, v97
	v_lshl_add_u64 v[16:17], v[16:17], 0, v[180:181]
	global_load_dwordx4 v[118:121], v[16:17], off
	global_load_dwordx4 v[114:117], v[16:17], off offset:32
	global_load_dwordx4 v[126:129], v[16:17], off offset:64
	global_load_dwordx4 v[122:125], v[16:17], off offset:96
	global_load_dwordx4 v[110:113], v[16:17], off offset:128
	global_load_dwordx4 v[106:109], v[16:17], off offset:160
	global_load_dwordx4 v[102:105], v[16:17], off offset:192
	global_load_dwordx4 v[98:101], v[16:17], off offset:224
	v_and_b32_e32 v25, 0xfffff0, v18
	v_lshlrev_b32_e32 v26, 1, v18
	v_and_or_b32 v25, v26, 8, v25
	v_and_b32_e32 v26, 0xfffff0, v21
	v_lshlrev_b32_e32 v21, 1, v21
	v_and_b32_e32 v24, 0x70, v64
	v_bfe_u32 v67, v64, 8, 1
	v_lshl_or_b32 v24, v67, 7, v24
	v_lshrrev_b32_e32 v27, 1, v18
	v_bfe_u32 v19, v19, 5, 2
	v_and_b32_e32 v18, 3, v18
	v_lshrrev_b32_e32 v25, 1, v25
	v_and_or_b32 v21, v21, 8, v26
	v_and_or_b32 v18, v27, 4, v18
	v_and_b32_e32 v27, 48, v20
	v_bitop3_b32 v22, v20, v22, v24 bitop3:0xde
	v_bitop3_b32 v20, v20, v23, v24 bitop3:0xde
	v_or_b32_e32 v23, v25, v19
	v_lshrrev_b32_e32 v21, 1, v21
	v_lshlrev_b32_e32 v18, 6, v18
	v_add_u32_e32 v203, 0, v20
	v_lshlrev_b32_e32 v20, 9, v23
	v_or_b32_e32 v19, v21, v19
	v_and_b32_e32 v198, 31, v64
	v_lshlrev_b32_e32 v49, 4, v64
	v_or3_b32 v16, v20, v18, v27
	v_lshlrev_b32_e32 v17, 9, v19
	v_lshlrev_b32_e32 v65, 8, v198
	v_and_b32_e32 v66, 0x70, v49
	v_bfe_u32 v67, v64, 4, 1
	v_lshl_or_b32 v66, v67, 7, v66
	v_or3_b32 v17, v17, v18, v27
	v_add_u32_e32 v204, 0, v16
	v_add_u32_e32 v202, 0, v22
	s_waitcnt vmcnt(0)
	v_add_u32_e32 v205, 0, v17
	s_add_i32 s3, 0, 0x10000
	s_cmp_lg_u32 0, -1
	v_and_b32_e32 v182, 0xffffffe0, v48
	v_and_b32_e32 v68, 63, v64
	s_mov_b32 s68, s69
	s_mov_b32 s70, s69
	s_mov_b32 s71, s69
	s_mov_b32 s72, s69
	s_mov_b32 s73, s69
	s_mov_b32 s74, s69
	s_mov_b32 s75, s69
	s_mov_b32 s76, s69
	s_waitcnt vmcnt(0) lgkmcnt(0)
	ds_write_b128 v204, v[0:3]
	ds_write_b128 v205, v[4:7]
	ds_write_b128 v202, v[8:11] offset:32768
	ds_write_b128 v203, v[12:15] offset:32768
	v_bitop3_b32 v0, v180, v65, v66 bitop3:0xde
	v_add_u32_e32 v206, 0, v0
	s_waitcnt lgkmcnt(0)
	s_barrier
	ds_read_b128 v[0:3], v206 offset:32768
	ds_read_b128 v[4:7], v206 offset:40960
	s_waitcnt lgkmcnt(1)
	v_mfma_f32_32x32x16_bf16 v[16:31], v[0:3], v[118:121], 0
	v_or_b32_e32 v0, 32, v180
	v_bitop3_b32 v0, v0, v65, v66 bitop3:0xde
	v_add_u32_e32 v211, 0, v0
	v_and_b32_e32 v9, 0xc0, v49
	v_lshlrev_b32_e32 v8, 3, v68
	s_mov_b32 s77, s69
	s_mov_b32 s78, s69
	s_waitcnt lgkmcnt(0)
	v_mfma_f32_32x32x16_bf16 v[32:47], v[4:7], v[118:121], 0
	ds_read_b128 v[0:3], v211 offset:32768
	ds_read_b128 v[4:7], v211 offset:40960
	s_mov_b32 s79, s69
	s_mov_b32 s80, s69
	s_mov_b32 s81, s69
	s_mov_b32 s82, s69
	s_mov_b32 s83, s69
	s_mov_b32 s30, 4
	s_waitcnt lgkmcnt(1)
	v_mfma_f32_32x32x16_bf16 v[16:31], v[0:3], v[114:117], v[16:31]
	v_or_b32_e32 v0, 64, v180
	v_bitop3_b32 v0, v0, v65, v66 bitop3:0xde
	v_add_u32_e32 v210, 0, v0
	v_mov_b32_e32 v199, 0
	s_waitcnt lgkmcnt(0)
	v_mfma_f32_32x32x16_bf16 v[32:47], v[4:7], v[114:117], v[32:47]
	ds_read_b128 v[0:3], v210 offset:32768
	ds_read_b128 v[4:7], v210 offset:40960
	s_waitcnt lgkmcnt(1)
	v_mfma_f32_32x32x16_bf16 v[16:31], v[0:3], v[126:129], v[16:31]
	v_or_b32_e32 v0, 0x60, v180
	v_bitop3_b32 v0, v0, v65, v66 bitop3:0xde
	v_add_u32_e32 v209, 0, v0
	s_waitcnt lgkmcnt(0)
	v_mfma_f32_32x32x16_bf16 v[32:47], v[4:7], v[126:129], v[32:47]
	ds_read_b128 v[0:3], v209 offset:32768
	ds_read_b128 v[4:7], v209 offset:40960
	s_waitcnt lgkmcnt(1)
	v_mfma_f32_32x32x16_bf16 v[16:31], v[0:3], v[122:125], v[16:31]
	v_or_b32_e32 v0, 0x80, v180
	v_bitop3_b32 v0, v0, v65, v66 bitop3:0xde
	v_add_u32_e32 v208, 0, v0
	ds_read_b128 v[0:3], v208 offset:32768
	s_waitcnt lgkmcnt(1)
	v_mfma_f32_32x32x16_bf16 v[32:47], v[4:7], v[122:125], v[32:47]
	ds_read_b128 v[4:7], v208 offset:40960
	s_waitcnt lgkmcnt(1)
	v_mfma_f32_32x32x16_bf16 v[16:31], v[0:3], v[110:113], v[16:31]
	v_or_b32_e32 v1, 0xa0, v180
	v_bitop3_b32 v1, v1, v65, v66 bitop3:0xde
	v_and_b32_e32 v0, 0x3fffffc0, v64
	v_add_u32_e32 v207, 0, v1
	v_lshl_add_u32 v181, v0, 2, s3
	ds_read_b128 v[0:3], v207 offset:32768
	s_cselect_b32 s3, 0, 0
	s_add_u32 s20, s0, 0x4000
	s_addc_u32 s21, s1, 0
	s_add_u32 s24, s4, 0x4000
	s_waitcnt lgkmcnt(1)
; #define SWRITE(b, i) do { *(bf16x8*)((char*)V_lds + (b) * SHM_V + vst0) = sr_[i].vs0;          \
;     *(bf16x8*)((char*)V_lds + (b) * SHM_V + vst1) = sr_[i].vs1; int kc = sc * 2;               \
;     *(bf16x8*)((char*)K_lds + (b) * SHM_K + KSWZ(sr, kc)) = sr_[i].ks0;                       \
;     *(bf16x8*)((char*)K_lds + (b) * SHM_K + KSWZ(32 + sr, kc)) = sr_[i].ks1; } while (0)
; #define SWAIT() asm volatile("s_waitcnt vmcnt(4)" ::: "memory")
; __device__ __forceinline__ void partialSM(f32x16& p0, f32x16& p1, float& m_reg, float& mn, float& alpha) {
;   constexpr float C = SCALE * 1.4426950408889634f;
;   float pmax = p0[0];
; #pragma unroll
;   for (int r = 1; r < 16; ++r) pmax = fmaxf(pmax, p0[r]);
; #pragma unroll
;   for (int r = 0; r < 16; ++r) pmax = fmaxf(pmax, p1[r]);
;   { auto rr = __builtin_amdgcn_permlane32_swap(__float_as_uint(pmax), __float_as_uint(pmax), false, false);
;     pmax = fmaxf(__uint_as_float(rr[0]), __uint_as_float(rr[1])); }
;   if (__builtin_expect(__all(pmax - m_reg <= THR / SCALE), 1)) { mn = m_reg; alpha = 1.f; }
;   else { mn = fmaxf(m_reg, pmax); alpha = __builtin_amdgcn_exp2f((m_reg - mn) * C); m_reg = mn; }
;   float mnC = -mn * C;
; #pragma unroll
;   for (int r = 0; r < 16; ++r) p0[r] = fmaf(p0[r], C, mnC);
; #pragma unroll
;   for (int r = 0; r < 16; ++r) p1[r] = fmaf(p1[r], C, mnC);
; #pragma unroll
;   for (int r = 0; r < 16; ++r) p0[r] = __builtin_amdgcn_exp2f(p0[r]);
; }
; __device__ __forceinline__ void attn_body(const bf16_t* __restrict__ Qb, const bf16_t* __restrict__ Kh, const bf16_t* __restrict__ Vh,
;                                           bf16_t* __restrict__ Ob, const bf16_t* __restrict__ AGb, int seq, char* lds) {
;     ...
;   qkt(pA0, pA1, K_lds, qr, r32, hi); partialSM(pA0, pA1, m_reg, mnA, alA);
;   SLOAD(SO, KVBLK); if (2 < NT) SLOAD(SE, 2 * KVBLK);
;   SWAIT(); SWRITE(1, SO); __syncthreads();
	v_mfma_f32_32x32x16_bf16 v[32:47], v[4:7], v[110:113], v[32:47]
	ds_read_b128 v[4:7], v207 offset:40960
	s_addc_u32 s25, s5, 0
	s_add_u32 s4, s4, 0x8000
	s_addc_u32 s5, s5, 0
	s_add_u32 s0, s0, 0x8000
	s_addc_u32 s1, s1, 0
	v_lshl_add_u32 v183, v198, 2, v181
	s_waitcnt lgkmcnt(1)
	v_mfma_f32_32x32x16_bf16 v[16:31], v[0:3], v[106:109], v[16:31]
	v_lshl_add_u64 v[0:1], s[20:21], 0, v[96:97]
	v_lshl_add_u64 v[2:3], s[20:21], 0, v[184:185]
	global_load_dwordx4 v[48:51], v[0:1], off
	global_load_dwordx4 v[52:55], v[2:3], off
	v_lshl_add_u64 v[0:1], s[24:25], 0, v[96:97]
	v_lshl_add_u64 v[2:3], s[24:25], 0, v[184:185]
	global_load_dwordx4 v[56:59], v[0:1], off
	global_load_dwordx4 v[60:63], v[2:3], off
	v_or_b32_e32 v0, 0xc0, v180
	v_bitop3_b32 v0, v0, v65, v66 bitop3:0xde
	v_add_u32_e32 v213, 0, v0
	ds_read_b128 v[0:3], v213 offset:32768
	s_waitcnt lgkmcnt(0)
	v_mfma_f32_32x32x16_bf16 v[32:47], v[4:7], v[106:109], v[32:47]
	v_lshlrev_b32_e32 v5, 1, v64
	v_and_or_b32 v4, v8, 24, v9
	v_and_b32_e32 v5, 32, v5
	v_and_b32_e32 v6, 0x100, v8
	v_or3_b32 v69, v4, v5, v6
	ds_read_b128 v[4:7], v213 offset:40960
	v_add_u32_e32 v201, s3, v69
	v_mfma_f32_32x32x16_bf16 v[16:31], v[0:3], v[102:105], v[16:31]
	v_or_b32_e32 v0, 0xe0, v180
	v_bitop3_b32 v0, v0, v65, v66 bitop3:0xde
	v_add_u32_e32 v212, 0, v0
	ds_read_b128 v[0:3], v212 offset:32768
	ds_read_b128 v[64:67], v212 offset:40960
	s_waitcnt lgkmcnt(0)
	v_mfma_f32_32x32x16_bf16 v[32:47], v[4:7], v[102:105], v[32:47]
	v_mfma_f32_32x32x16_bf16 v[16:31], v[0:3], v[98:101], v[16:31]
	v_mov_b64_e32 v[0:1], s[68:69]
	v_mov_b64_e32 v[14:15], s[82:83]
	v_mov_b64_e32 v[2:3], s[70:71]
	v_mov_b64_e32 v[4:5], s[72:73]
	v_mov_b64_e32 v[6:7], s[74:75]
	v_mov_b64_e32 v[8:9], s[76:77]
	v_mov_b64_e32 v[10:11], s[78:79]
	v_mfma_f32_32x32x16_bf16 v[32:47], v[64:67], v[98:101], v[32:47]
	s_nop 3
	v_max_f32_e32 v64, v17, v17
	v_max_f32_e32 v65, v16, v16
	v_max_f32_e32 v64, v65, v64
	v_max3_f32 v64, v64, v18, v19
	v_max3_f32 v64, v64, v20, v21
	v_max3_f32 v64, v64, v22, v23
	v_max3_f32 v64, v64, v24, v25
	v_max3_f32 v64, v64, v26, v27
	v_max3_f32 v64, v64, v28, v29
	v_max3_f32 v64, v64, v30, v31
	v_max3_f32 v64, v64, v32, v33
	v_max3_f32 v64, v64, v34, v35
	v_max3_f32 v64, v64, v36, v37
	v_max3_f32 v70, v64, v38, v39
	v_lshl_add_u64 v[64:65], s[4:5], 0, v[184:185]
	v_lshl_add_u64 v[66:67], s[4:5], 0, v[96:97]
	global_load_dwordx4 v[142:145], v[64:65], off
	global_load_dwordx4 v[138:141], v[66:67], off
	v_lshl_add_u64 v[64:65], s[0:1], 0, v[184:185]
	v_lshl_add_u64 v[66:67], s[0:1], 0, v[96:97]
	global_load_dwordx4 v[134:137], v[64:65], off
	global_load_dwordx4 v[130:133], v[66:67], off
	v_max3_f32 v64, v70, v40, v41
	v_max3_f32 v64, v64, v42, v43
	v_max3_f32 v64, v64, v44, v45
	v_max3_f32 v64, v64, v46, v47
	v_mov_b32_e32 v65, v64
	s_nop 1
	v_permlane32_swap_b32_e32 v64, v65
	v_max_f32_e32 v65, v65, v65
	v_max_f32_e32 v64, v64, v64
	v_max_f32_e32 v64, v64, v65
	v_add_f32_e32 v65, 0x7149f2ca, v64
	v_cmp_ge_f32_e32 vcc, s62, v65
	s_cmp_eq_u64 vcc, exec
	s_waitcnt vmcnt(4)
	ds_write_b128 v204, v[48:51] offset:16384
	ds_write_b128 v205, v[52:55] offset:16384
	ds_write_b128 v202, v[56:59] offset:49152
	ds_write_b128 v203, v[60:63] offset:49152
	v_max_f32_e32 v48, 0xf149f2ca, v64
	s_cselect_b64 vcc, -1, 0
	v_cndmask_b32_e32 v170, v48, v194, vcc
	v_sub_f32_e32 v49, 0xf149f2ca, v48
	v_mul_f32_e32 v48, 0xbe0293ee, v170
	v_fmamk_f32 v16, v16, 0x3e0293ee, v48
	v_exp_f32_e32 v163, v16
	v_fmamk_f32 v16, v17, 0x3e0293ee, v48
	v_exp_f32_e32 v177, v16
	v_fmamk_f32 v16, v18, 0x3e0293ee, v48
	v_exp_f32_e32 v164, v16
	v_fmamk_f32 v16, v19, 0x3e0293ee, v48
	v_exp_f32_e32 v186, v16
	v_fmamk_f32 v16, v20, 0x3e0293ee, v48
	v_exp_f32_e32 v176, v16
	v_fmamk_f32 v16, v21, 0x3e0293ee, v48
	v_exp_f32_e32 v187, v16
	v_fmamk_f32 v16, v22, 0x3e0293ee, v48
	v_exp_f32_e32 v165, v16
	v_fmamk_f32 v16, v23, 0x3e0293ee, v48
	v_exp_f32_e32 v175, v16
	v_fmamk_f32 v16, v24, 0x3e0293ee, v48
	v_mul_f32_e32 v49, 0x3e0293ee, v49
	v_exp_f32_e32 v166, v16
	v_fmamk_f32 v16, v25, 0x3e0293ee, v48
	v_exp_f32_e32 v49, v49
	v_exp_f32_e32 v173, v16
	v_fmamk_f32 v16, v26, 0x3e0293ee, v48
	v_exp_f32_e32 v167, v16
	v_fmamk_f32 v16, v27, 0x3e0293ee, v48
	v_exp_f32_e32 v174, v16
	v_fmamk_f32 v16, v28, 0x3e0293ee, v48
	v_exp_f32_e32 v168, v16
	v_fmamk_f32 v16, v29, 0x3e0293ee, v48
	v_pk_fma_f32 v[146:147], v[46:47], s[6:7], v[48:49] op_sel_hi:[1,0,0]
	v_pk_fma_f32 v[152:153], v[44:45], s[6:7], v[48:49] op_sel_hi:[1,0,0]
	v_pk_fma_f32 v[156:157], v[42:43], s[6:7], v[48:49] op_sel_hi:[1,0,0]
	v_pk_fma_f32 v[148:149], v[40:41], s[6:7], v[48:49] op_sel_hi:[1,0,0]
	v_pk_fma_f32 v[150:151], v[38:39], s[6:7], v[48:49] op_sel_hi:[1,0,0]
	v_pk_fma_f32 v[154:155], v[36:37], s[6:7], v[48:49] op_sel_hi:[1,0,0]
	v_pk_fma_f32 v[158:159], v[34:35], s[6:7], v[48:49] op_sel_hi:[1,0,0]
	v_pk_fma_f32 v[160:161], v[32:33], s[6:7], v[48:49] op_sel_hi:[1,0,0]
	v_exp_f32_e32 v171, v16
	v_fmamk_f32 v16, v30, 0x3e0293ee, v48
	v_fmac_f32_e32 v48, 0x3e0293ee, v31
	v_exp_f32_e32 v169, v16
	v_exp_f32_e32 v172, v48
	s_addk_i32 s3, 0x4000
	v_mov_b64_e32 v[12:13], s[80:81]
	v_cndmask_b32_e64 v214, v49, 1.0, vcc
	s_add_u32 s20, s54, s23
	v_mov_b64_e32 v[62:63], v[14:15]
	v_mov_b64_e32 v[46:47], v[14:15]
	v_mov_b64_e32 v[30:31], v[14:15]
	v_cmp_gt_u32_e64 s[4:5], 32, v68
	v_add_u32_e32 v200, s3, v69
	s_addc_u32 s21, s55, s22
	v_mov_b64_e32 v[60:61], v[12:13]
	v_mov_b64_e32 v[58:59], v[10:11]
	v_mov_b64_e32 v[56:57], v[8:9]
	v_mov_b64_e32 v[54:55], v[6:7]
	v_mov_b64_e32 v[52:53], v[4:5]
	v_mov_b64_e32 v[50:51], v[2:3]
	v_mov_b64_e32 v[48:49], v[0:1]
	v_mov_b64_e32 v[44:45], v[12:13]
	v_mov_b64_e32 v[42:43], v[10:11]
	v_mov_b64_e32 v[40:41], v[8:9]
	v_mov_b64_e32 v[38:39], v[6:7]
	v_mov_b64_e32 v[36:37], v[4:5]
	v_mov_b64_e32 v[34:35], v[2:3]
	v_mov_b64_e32 v[32:33], v[0:1]
	v_mov_b64_e32 v[28:29], v[12:13]
	v_mov_b64_e32 v[26:27], v[10:11]
	v_mov_b64_e32 v[24:25], v[8:9]
	v_mov_b64_e32 v[22:23], v[6:7]
	v_mov_b64_e32 v[20:21], v[4:5]
	v_mov_b64_e32 v[18:19], v[2:3]
	v_mov_b64_e32 v[16:17], v[0:1]
	s_waitcnt lgkmcnt(0)
	s_barrier
